# cmp/window attention passes: packed f32 adds/muls split into scalar ops (same arithmetic)
# speedup vs baseline: 1.0485x; 1.0020x over previous
; template <int DQK, int MODE, bool FULL, int I0, int NQ> __device__ __forceinline__ void tile_x(LAS unsigned char* lds, const bf16x8 (&qf)[2][DQK / 32], int kbase, const int (&tpos)[2], const bool (&rowsel)[2],
;         float (&m)[2], float (&l)[2], f32x4 (&o)[2][4], f32x4 (&s)[2][4], int fr, int fq) {
;     ...
;     for (int q = 0; q < NQ; ++q) { meff[q] = (m[I0 + q] > -1e29f) ? m[I0 + q] : 0.f; const float c = (MODE == SEL && !rowsel[I0 + q]) ? NEG : -meff[q];
; #pragma unroll
;         for (int ss = 0; ss < 4; ++ss) s[I0 + q][ss] = (f32x4){c, c, c, c}; }
; #pragma unroll
;     for (int ss = 0; ss < 4; ++ss)
; #pragma unroll
;         for (int ks = 0; ks < NKS; ++ks) {
;             const bf16x8 kf = *(const LAS bf16x8*)(lds + k_off<DQK>(16 * ss + fr, 4 * ks + fq));
; #pragma unroll
;             for (int q = 0; q < NQ; ++q) s[I0 + q][ss] = __builtin_amdgcn_mfma_f32_16x16x32_bf16(kf, qf[I0 + q][ks], s[I0 + q][ss], 0, 0, 0);
;         }
; #pragma unroll
;     for (int q = 0; q < NQ; ++q) {
;         f32x4 (&sq)[4] = s[I0 + q];
;         const float mo = m[I0 + q];
;         bool slow = true;
;         if (FULL) {
;             int ia = __builtin_bit_cast(int, sq[0][0]);
;     ...
;             ia = IMX3(ia, sq[0][1], sq[0][2]); ia = IMX3(ia, sq[0][3], sq[1][0]); ia = IMX3(ia, sq[1][1], sq[1][2]); ia = IMX3(ia, sq[1][3], sq[2][0]);
;             int ib = __builtin_bit_cast(int, sq[2][1]);
;             ib = IMX3(ib, sq[2][2], sq[2][3]); ib = IMX3(ib, sq[3][0], sq[3][1]); ib = IMX3(ib, sq[3][2], sq[3][3]);
;     ...
;             const bool big = !(mo > -1e29f) || (imax2(ia, ib) > __builtin_bit_cast(int, RESCALE_THR));
;             slow = __any(big ? 1 : 0) != 0;
;         }
;         if (slow) {
;             float mx;
;             if (FULL) {
;                 mx = fmaxf(fmaxf(sq[0][0], sq[0][1]), fmaxf(sq[0][2], sq[0][3]));
; #pragma unroll
;                 for (int ss = 1; ss < 4; ++ss) mx = fmaxf(mx, fmaxf(fmaxf(sq[ss][0], sq[ss][1]), fmaxf(sq[ss][2], sq[ss][3])));
;             } else {
;                 mx = NEG;
; #pragma unroll
;                 for (int ss = 0; ss < 4; ++ss)
; #pragma unroll
;                     for (int i = 0; i < 4; ++i) { const bool ok = key_ok<MODE>(kbase + 16 * ss + 4 * fq + i, tpos[I0 + q], rowsel[I0 + q]); const float v = ok ? sq[ss][i] : NEG; sq[ss][i] = v; mx = fmaxf(mx, v); }
;             }
;             mx = rows_max(mx);
.LBB0_995:
	s_mul_i32 s67, s66, 0x4800
	s_add_i32 s6, s21, 31
	s_add_i32 s87, s67, 0
	v_cmp_le_u32_e64 s[6:7], s6, v136
	s_and_saveexec_b64 s[60:61], s[6:7]
	s_cbranch_execz .LBB0_1010
	v_add_u32_e32 v56, s87, v120
	v_add_u32_e32 v135, v56, v121
	s_add_i32 s8, s21, 0x40f
	v_add_u32_e32 v134, v56, v122
	s_waitcnt lgkmcnt(0)
	ds_read_b128 v[100:103], v135
	ds_read_b128 v[96:99], v134
	v_cmp_le_u32_e32 vcc, s8, v113
	v_cmp_lt_f32_e64 s[10:11], s77, v111
	v_cmp_lt_f32_e64 s[8:9], s77, v110
	s_nop 0
	v_cndmask_b32_e64 v133, 0, v111, s[10:11]
	v_cndmask_b32_e64 v132, 0, v110, s[8:9]
	v_xor_b32_e32 v88, 0x80000000, v133
	v_xor_b32_e32 v92, 0x80000000, v132
	v_mov_b32_e32 v89, v88
	v_mov_b32_e32 v90, v88
	v_mov_b32_e32 v91, v88
	v_mov_b32_e32 v93, v92
	v_mov_b32_e32 v94, v92
	v_mov_b32_e32 v95, v92
	s_and_saveexec_b64 s[12:13], vcc
	s_xor_b64 s[62:63], exec, s[12:13]
	s_cbranch_execz .LBB0_1004
	s_waitcnt lgkmcnt(0)
	v_mfma_f32_16x16x32_bf16 v[60:63], v[100:103], v[8:11], v[92:95]
	v_cmp_nlt_f32_e64 s[12:13], s77, v111
	v_mfma_f32_16x16x32_bf16 v[72:75], v[96:99], v[12:15], v[60:63]
	s_nop 5
	ds_read_b128 v[60:63], v135 offset:2048
	ds_read_b128 v[64:67], v135 offset:4096
	ds_read_b128 v[80:83], v134 offset:2048
	ds_read_b128 v[84:87], v135 offset:6144
	v_mfma_f32_16x16x32_bf16 v[56:59], v[100:103], v[0:3], v[88:91]
	s_waitcnt lgkmcnt(0)
	v_mfma_f32_16x16x32_bf16 v[68:71], v[60:63], v[0:3], v[88:91]
	v_mfma_f32_16x16x32_bf16 v[56:59], v[96:99], v[4:7], v[56:59]
	ds_read_b128 v[96:99], v134 offset:4096
	ds_read_b128 v[100:103], v134 offset:6144
	v_mfma_f32_16x16x32_bf16 v[76:79], v[60:63], v[8:11], v[92:95]
	v_mfma_f32_16x16x32_bf16 v[60:63], v[80:83], v[4:7], v[68:71]
	v_mfma_f32_16x16x32_bf16 v[68:71], v[64:67], v[0:3], v[88:91]
	v_mfma_f32_16x16x32_bf16 v[76:79], v[80:83], v[12:15], v[76:79]
	v_mfma_f32_16x16x32_bf16 v[80:83], v[64:67], v[8:11], v[92:95]
	s_waitcnt lgkmcnt(0)
	v_mfma_f32_16x16x32_bf16 v[64:67], v[96:99], v[4:7], v[68:71]
	v_mfma_f32_16x16x32_bf16 v[68:71], v[84:87], v[0:3], v[88:91]
	v_mfma_f32_16x16x32_bf16 v[84:87], v[84:87], v[8:11], v[92:95]
	s_nop 1
	v_max_i32_e32 v88, v56, v60
	v_mfma_f32_16x16x32_bf16 v[68:71], v[100:103], v[4:7], v[68:71]
	v_mfma_f32_16x16x32_bf16 v[80:83], v[96:99], v[12:15], v[80:83]
	v_mfma_f32_16x16x32_bf16 v[84:87], v[100:103], v[12:15], v[84:87]
	s_nop 5
	v_max3_i32 v88, v64, v68, v88
	v_cmp_lt_i32_e32 vcc, s80, v88
	s_or_b64 vcc, s[12:13], vcc
	s_cbranch_vccz .LBB0_1000
	v_max_f32_e32 v88, v57, v57
	v_max_f32_e32 v89, v56, v56
	v_max_f32_e32 v88, v89, v88
	v_max_f32_e32 v89, v59, v59
	v_max_f32_e32 v90, v58, v58
	v_max_f32_e32 v89, v90, v89
	v_max_f32_e32 v90, v63, v63
	v_max_f32_e32 v91, v62, v62
	v_max_f32_e32 v90, v91, v90
	v_max3_f32 v90, v60, v61, v90
	v_max3_f32 v88, v88, v89, v90
	v_max_f32_e32 v89, v67, v67
	v_max_f32_e32 v90, v66, v66
	v_max_f32_e32 v89, v90, v89
	v_max_f32_e32 v90, v71, v71
	v_max_f32_e32 v91, v70, v70
	v_max_f32_e32 v90, v91, v90
	v_max3_f32 v89, v64, v65, v89
	v_max3_f32 v90, v68, v69, v90
	v_max3_f32 v88, v88, v89, v90
	v_mov_b32_e32 v89, v88
	s_nop 1
	v_permlane16_swap_b32_e32 v88, v89
	v_max_f32_e32 v89, v89, v89
	v_max_f32_e32 v88, v88, v88
	v_max_f32_e32 v88, v88, v89
	v_mov_b32_e32 v89, v88
	s_nop 1
	v_permlane32_swap_b32_e32 v88, v89
	v_max_f32_e32 v89, v89, v89
	v_max_f32_e32 v88, v88, v88
	v_max_f32_e32 v88, v88, v89
	v_cmp_lt_f32_e32 vcc, s77, v88
	s_nop 1
	v_cndmask_b32_e64 v89, 0, 1, vcc
	v_cmp_lt_f32_e32 vcc, s80, v88
	s_nop 1
	v_cndmask_b32_e64 v90, 0, 1, vcc
	v_cndmask_b32_e64 v89, v90, v89, s[12:13]
	v_and_b32_e32 v89, 1, v89
	v_cmp_eq_u32_e64 s[12:13], 1, v89
	v_cmp_ne_u32_e32 vcc, 0, v89
	s_cbranch_vccz .LBB0_1000
	v_add_f32_e32 v89, v133, v88
	v_cndmask_b32_e64 v89, v111, v89, s[12:13]
	v_sub_f32_e32 v90, v111, v89
	v_exp_f32_e32 v90, v90
	v_cndmask_b32_e64 v88, 0, v88, s[12:13]
	v_sub_f32_e32 v56, v56, v88
	v_sub_f32_e32 v57, v57, v88
	v_cndmask_b32_e64 v90, 1.0, v90, s[12:13]
	v_mul_f32_e32 v104, v104, v90
	v_mul_f32_e32 v46, v46, v90
	v_mul_f32_e32 v47, v47, v90
	v_mul_f32_e32 v44, v44, v90
	v_mul_f32_e32 v45, v45, v90
	v_mul_f32_e32 v42, v42, v90
	v_mul_f32_e32 v43, v43, v90
	v_mul_f32_e32 v40, v40, v90
	v_mul_f32_e32 v41, v41, v90
	v_mul_f32_e32 v38, v38, v90
	v_mul_f32_e32 v39, v39, v90
	v_mul_f32_e32 v36, v36, v90
	v_mul_f32_e32 v37, v37, v90
	v_mul_f32_e32 v34, v34, v90
	v_mul_f32_e32 v35, v35, v90
	v_mul_f32_e32 v32, v32, v90
	v_mul_f32_e32 v33, v33, v90
	v_sub_f32_e32 v58, v58, v88
	v_sub_f32_e32 v59, v59, v88
	v_sub_f32_e32 v60, v60, v88
	v_sub_f32_e32 v61, v61, v88
	v_sub_f32_e32 v62, v62, v88
	v_sub_f32_e32 v63, v63, v88
	v_sub_f32_e32 v64, v64, v88
	v_sub_f32_e32 v65, v65, v88
	v_sub_f32_e32 v66, v66, v88
	v_sub_f32_e32 v67, v67, v88
	v_sub_f32_e32 v68, v68, v88
	v_sub_f32_e32 v69, v69, v88
	v_sub_f32_e32 v70, v70, v88
	v_sub_f32_e32 v71, v71, v88
	v_mov_b32_e32 v111, v89
; #define IMX3(a, b, c) imax2(imax2((a), __builtin_bit_cast(int, (b))), __builtin_bit_cast(int, (c)))
; template <int DQK, int MODE, bool FULL, int I0, int NQ> __device__ __forceinline__ void tile_x(LAS unsigned char* lds, const bf16x8 (&qf)[2][DQK / 32], int kbase, const int (&tpos)[2], const bool (&rowsel)[2],
;         float (&m)[2], float (&l)[2], f32x4 (&o)[2][4], f32x4 (&s)[2][4], int fr, int fq) {
;     ...
;     for (int q = 0; q < NQ; ++q) {
;         f32x4 (&sq)[4] = s[I0 + q];
;         const float mo = m[I0 + q];
;         bool slow = true;
;         if (FULL) {
;             int ia = __builtin_bit_cast(int, sq[0][0]);
;     ...
;             ia = IMX3(ia, sq[0][1], sq[0][2]); ia = IMX3(ia, sq[0][3], sq[1][0]); ia = IMX3(ia, sq[1][1], sq[1][2]); ia = IMX3(ia, sq[1][3], sq[2][0]);
;             int ib = __builtin_bit_cast(int, sq[2][1]);
;             ib = IMX3(ib, sq[2][2], sq[2][3]); ib = IMX3(ib, sq[3][0], sq[3][1]); ib = IMX3(ib, sq[3][2], sq[3][3]);
;     ...
;             const bool big = !(mo > -1e29f) || (imax2(ia, ib) > __builtin_bit_cast(int, RESCALE_THR));
;             slow = __any(big ? 1 : 0) != 0;
;         }
;         if (slow) {
;             float mx;
;             if (FULL) {
;                 mx = fmaxf(fmaxf(sq[0][0], sq[0][1]), fmaxf(sq[0][2], sq[0][3]));
; #pragma unroll
;                 for (int ss = 1; ss < 4; ++ss) mx = fmaxf(mx, fmaxf(fmaxf(sq[ss][0], sq[ss][1]), fmaxf(sq[ss][2], sq[ss][3])));
;             } else {
;                 mx = NEG;
; #pragma unroll
;                 for (int ss = 0; ss < 4; ++ss)
; #pragma unroll
;                     for (int i = 0; i < 4; ++i) { const bool ok = key_ok<MODE>(kbase + 16 * ss + 4 * fq + i, tpos[I0 + q], rowsel[I0 + q]); const float v = ok ? sq[ss][i] : NEG; sq[ss][i] = v; mx = fmaxf(mx, v); }
;             }
;             mx = rows_max(mx);
;             const bool need = (mo > -1e29f) ? (mx > RESCALE_THR) : (mx > -1e29f);
;             if (__any(need ? 1 : 0)) {
;                 const float delta = need ? mx : 0.f; const float mnew = need ? meff[q] + delta : mo; const float alpha = need ? __builtin_amdgcn_exp2f(mo - mnew) : 1.0f;
;                 l[I0 + q] *= alpha; m[I0 + q] = mnew;
; #pragma unroll
;                 for (int dt = 0; dt < 4; ++dt) o[I0 + q][dt] = o[I0 + q][dt] * alpha;
; #pragma unroll
;                 for (int ss = 0; ss < 4; ++ss) sq[ss] = sq[ss] - delta;
;             }
.LBB0_1000:
	v_max_i32_e32 v88, v72, v76
	v_max3_i32 v88, v80, v84, v88
	v_cmp_nlt_f32_e64 s[12:13], s77, v110
	v_cmp_lt_i32_e32 vcc, s80, v88
	s_or_b64 vcc, s[12:13], vcc
	s_cbranch_vccz .LBB0_1003
	v_max_f32_e32 v88, v73, v73
	v_max_f32_e32 v89, v72, v72
	v_max_f32_e32 v88, v89, v88
	v_max_f32_e32 v89, v75, v75
	v_max_f32_e32 v90, v74, v74
	v_max_f32_e32 v89, v90, v89
	v_max_f32_e32 v90, v79, v79
	v_max_f32_e32 v91, v78, v78
	v_max_f32_e32 v90, v91, v90
	v_max3_f32 v90, v76, v77, v90
	v_max3_f32 v88, v88, v89, v90
	v_max_f32_e32 v89, v83, v83
	v_max_f32_e32 v90, v82, v82
	v_max_f32_e32 v89, v90, v89
	v_max_f32_e32 v90, v87, v87
	v_max_f32_e32 v91, v86, v86
	v_max_f32_e32 v90, v91, v90
	v_max3_f32 v89, v80, v81, v89
	v_max3_f32 v90, v84, v85, v90
	v_max3_f32 v88, v88, v89, v90
	v_mov_b32_e32 v89, v88
	s_nop 1
	v_permlane16_swap_b32_e32 v88, v89
	v_max_f32_e32 v89, v89, v89
	v_max_f32_e32 v88, v88, v88
	v_max_f32_e32 v88, v88, v89
	v_mov_b32_e32 v89, v88
	s_nop 1
	v_permlane32_swap_b32_e32 v88, v89
	v_max_f32_e32 v89, v89, v89
	v_max_f32_e32 v88, v88, v88
	v_max_f32_e32 v88, v88, v89
	v_cmp_lt_f32_e32 vcc, s77, v88
	s_nop 1
	v_cndmask_b32_e64 v89, 0, 1, vcc
	v_cmp_lt_f32_e32 vcc, s80, v88
	s_nop 1
	v_cndmask_b32_e64 v90, 0, 1, vcc
	v_cndmask_b32_e64 v89, v90, v89, s[12:13]
	v_and_b32_e32 v89, 1, v89
	v_cmp_eq_u32_e64 s[12:13], 1, v89
	v_cmp_ne_u32_e32 vcc, 0, v89
	s_cbranch_vccz .LBB0_1003
	v_add_f32_e32 v89, v132, v88
	v_cndmask_b32_e64 v89, v110, v89, s[12:13]
	v_sub_f32_e32 v90, v110, v89
	v_exp_f32_e32 v90, v90
	v_cndmask_b32_e64 v88, 0, v88, s[12:13]
	v_sub_f32_e32 v72, v72, v88
	v_sub_f32_e32 v73, v73, v88
	v_cndmask_b32_e64 v90, 1.0, v90, s[12:13]
	v_mul_f32_e32 v105, v105, v90
	v_mul_f32_e32 v30, v30, v90
	v_mul_f32_e32 v31, v31, v90
	v_mul_f32_e32 v28, v28, v90
	v_mul_f32_e32 v29, v29, v90
	v_mul_f32_e32 v26, v26, v90
	v_mul_f32_e32 v27, v27, v90
	v_mul_f32_e32 v24, v24, v90
	v_mul_f32_e32 v25, v25, v90
	v_mul_f32_e32 v22, v22, v90
	v_mul_f32_e32 v23, v23, v90
	v_mul_f32_e32 v20, v20, v90
	v_mul_f32_e32 v21, v21, v90
	v_mul_f32_e32 v18, v18, v90
	v_mul_f32_e32 v19, v19, v90
	v_mul_f32_e32 v16, v16, v90
	v_mul_f32_e32 v17, v17, v90
	v_sub_f32_e32 v74, v74, v88
	v_sub_f32_e32 v75, v75, v88
	v_sub_f32_e32 v76, v76, v88
	v_sub_f32_e32 v77, v77, v88
	v_sub_f32_e32 v78, v78, v88
	v_sub_f32_e32 v79, v79, v88
	v_sub_f32_e32 v80, v80, v88
	v_sub_f32_e32 v81, v81, v88
	v_sub_f32_e32 v82, v82, v88
	v_sub_f32_e32 v83, v83, v88
	v_sub_f32_e32 v84, v84, v88
	v_sub_f32_e32 v85, v85, v88
	v_sub_f32_e32 v86, v86, v88
	v_sub_f32_e32 v87, v87, v88
	v_mov_b32_e32 v110, v89
.LBB0_1003:
.LBB0_1004:
	s_andn2_saveexec_b64 s[12:13], s[62:63]
	s_cbranch_execz .LBB0_1009
	s_waitcnt lgkmcnt(0)
	v_mfma_f32_16x16x32_bf16 v[56:59], v[100:103], v[0:3], v[88:91]
	ds_read_b128 v[64:67], v135 offset:2048
	ds_read_b128 v[68:71], v135 offset:4096
	ds_read_b128 v[76:79], v134 offset:2048
	ds_read_b128 v[84:87], v135 offset:6144
	v_add_u32_e32 v135, s21, v123
	ds_read_b128 v[80:83], v134 offset:4096
	ds_read_b128 v[138:141], v134 offset:6144
	v_mfma_f32_16x16x32_bf16 v[60:63], v[100:103], v[8:11], v[92:95]
	v_add_u32_e32 v101, 0x12f, v135
	v_add_u32_e32 v103, 0x14f, v135
	v_mfma_f32_16x16x32_bf16 v[56:59], v[96:99], v[4:7], v[56:59]
	v_mfma_f32_16x16x32_bf16 v[72:75], v[96:99], v[12:15], v[60:63]
	v_add_u32_e32 v96, 31, v135
	v_cmp_le_u32_e32 vcc, v96, v114
	v_add_u32_e32 v97, 47, v135
	s_waitcnt lgkmcnt(0)
	v_mfma_f32_16x16x32_bf16 v[60:63], v[64:67], v[0:3], v[88:91]
	s_nop 1
	v_cndmask_b32_e32 v56, v183, v56, vcc
	v_cmp_le_u32_e32 vcc, v97, v114
	v_add_u32_e32 v98, 63, v135
	v_add_u32_e32 v99, 0x4f, v135
	v_cndmask_b32_e32 v57, v183, v57, vcc
	v_cmp_le_u32_e32 vcc, v98, v114
	v_mfma_f32_16x16x32_bf16 v[64:67], v[64:67], v[8:11], v[92:95]
	v_max3_f32 v100, v56, s78, v57
	v_cndmask_b32_e32 v58, v183, v58, vcc
	v_cmp_le_u32_e32 vcc, v99, v114
	v_mfma_f32_16x16x32_bf16 v[60:63], v[76:79], v[4:7], v[60:63]
	s_nop 0
	v_cndmask_b32_e32 v59, v183, v59, vcc
	v_max3_f32 v102, v100, v58, v59
	v_add_u32_e32 v100, 0x11f, v135
	v_cmp_le_u32_e32 vcc, v100, v114
	v_mfma_f32_16x16x32_bf16 v[76:79], v[76:79], v[12:15], v[64:67]
	s_nop 1
	v_cndmask_b32_e32 v60, v183, v60, vcc
	v_cmp_le_u32_e32 vcc, v101, v114
	v_mfma_f32_16x16x32_bf16 v[64:67], v[68:71], v[0:3], v[88:91]
	s_nop 0
	v_cndmask_b32_e32 v61, v183, v61, vcc
	v_max3_f32 v134, v102, v60, v61
	v_mfma_f32_16x16x32_bf16 v[68:71], v[68:71], v[8:11], v[92:95]
	v_add_u32_e32 v102, 0x13f, v135
	v_cmp_le_u32_e32 vcc, v102, v114
	v_mfma_f32_16x16x32_bf16 v[64:67], v[80:83], v[4:7], v[64:67]
	s_nop 0
	v_cndmask_b32_e32 v62, v183, v62, vcc
	v_cmp_le_u32_e32 vcc, v103, v114
	v_mfma_f32_16x16x32_bf16 v[80:83], v[80:83], v[12:15], v[68:71]
	s_nop 0
	v_cndmask_b32_e32 v63, v183, v63, vcc
	v_max3_f32 v137, v134, v62, v63
	v_add_u32_e32 v134, 0x21f, v135
	v_mfma_f32_16x16x32_bf16 v[68:71], v[84:87], v[0:3], v[88:91]
	v_cmp_le_u32_e32 vcc, v134, v114
	s_nop 1
	v_add_u32_e32 v88, 0x22f, v135
	v_cndmask_b32_e32 v64, v183, v64, vcc
	v_cmp_le_u32_e32 vcc, v88, v114
	v_add_u32_e32 v89, 0x23f, v135
	v_add_u32_e32 v90, 0x24f, v135
	v_cndmask_b32_e32 v65, v183, v65, vcc
	v_cmp_le_u32_e32 vcc, v89, v114
	v_mfma_f32_16x16x32_bf16 v[68:71], v[138:141], v[4:7], v[68:71]
	v_max3_f32 v91, v137, v64, v65
	v_cndmask_b32_e32 v66, v183, v66, vcc
	v_cmp_le_u32_e32 vcc, v90, v114
	v_mfma_f32_16x16x32_bf16 v[84:87], v[84:87], v[8:11], v[92:95]
	s_nop 0
	v_cndmask_b32_e32 v67, v183, v67, vcc
	s_nop 0
	v_max3_f32 v93, v91, v66, v67
	v_add_u32_e32 v91, 0x31f, v135
	v_cmp_le_u32_e32 vcc, v91, v114
	v_add_u32_e32 v92, 0x32f, v135
	v_add_u32_e32 v94, 0x34f, v135
	v_cndmask_b32_e32 v68, v183, v68, vcc
	v_cmp_le_u32_e32 vcc, v92, v114
	v_mfma_f32_16x16x32_bf16 v[84:87], v[138:141], v[12:15], v[84:87]
	s_nop 0
	v_cndmask_b32_e32 v69, v183, v69, vcc
	v_max3_f32 v95, v93, v68, v69
	v_add_u32_e32 v93, 0x33f, v135
	v_cmp_le_u32_e32 vcc, v93, v114
	s_nop 1
	v_cndmask_b32_e32 v70, v183, v70, vcc
	v_cmp_le_u32_e32 vcc, v94, v114
	s_nop 1
	v_cndmask_b32_e32 v71, v183, v71, vcc
	v_max3_f32 v95, v95, v70, v71
	v_mov_b32_e32 v135, v95
	s_nop 1
	v_permlane16_swap_b32_e32 v95, v135
	v_max_f32_e32 v135, v135, v135
	v_max_f32_e32 v95, v95, v95
	v_max_f32_e32 v95, v95, v135
	v_mov_b32_e32 v135, v95
	s_nop 1
	v_permlane32_swap_b32_e32 v95, v135
	v_max_f32_e32 v135, v135, v135
	v_max_f32_e32 v95, v95, v95
	v_max_f32_e32 v95, v95, v135
	v_cmp_lt_f32_e32 vcc, s80, v95
	s_nop 1
	v_cndmask_b32_e64 v135, 0, 1, vcc
	v_cmp_lt_f32_e32 vcc, s77, v95
	s_nop 1
	v_cndmask_b32_e64 v137, 0, 1, vcc
	v_cndmask_b32_e64 v135, v137, v135, s[10:11]
	v_and_b32_e32 v135, 1, v135
	v_cmp_eq_u32_e64 s[10:11], 1, v135
	v_cmp_ne_u32_e32 vcc, 0, v135
	s_cbranch_vccz .LBB0_1007
; template <int DQK, int MODE, bool FULL, int I0, int NQ> __device__ __forceinline__ void tile_x(LAS unsigned char* lds, const bf16x8 (&qf)[2][DQK / 32], int kbase, const int (&tpos)[2], const bool (&rowsel)[2],
;         float (&m)[2], float (&l)[2], f32x4 (&o)[2][4], f32x4 (&s)[2][4], int fr, int fq) {
;     ...
;                 for (int ss = 0; ss < 4; ++ss)
; #pragma unroll
;                     for (int i = 0; i < 4; ++i) { const bool ok = key_ok<MODE>(kbase + 16 * ss + 4 * fq + i, tpos[I0 + q], rowsel[I0 + q]); const float v = ok ? sq[ss][i] : NEG; sq[ss][i] = v; mx = fmaxf(mx, v); }
;             }
;             mx = rows_max(mx);
;             const bool need = (mo > -1e29f) ? (mx > RESCALE_THR) : (mx > -1e29f);
;             if (__any(need ? 1 : 0)) {
;                 const float delta = need ? mx : 0.f; const float mnew = need ? meff[q] + delta : mo; const float alpha = need ? __builtin_amdgcn_exp2f(mo - mnew) : 1.0f;
;                 l[I0 + q] *= alpha; m[I0 + q] = mnew;
; #pragma unroll
;                 for (int dt = 0; dt < 4; ++dt) o[I0 + q][dt] = o[I0 + q][dt] * alpha;
; #pragma unroll
;                 for (int ss = 0; ss < 4; ++ss) sq[ss] = sq[ss] - delta;
;             }
	v_add_f32_e32 v133, v133, v95
	v_cndmask_b32_e64 v133, v111, v133, s[10:11]
	v_sub_f32_e32 v111, v111, v133
	v_exp_f32_e32 v111, v111
	v_cndmask_b32_e64 v95, 0, v95, s[10:11]
	v_sub_f32_e32 v56, v56, v95
	v_sub_f32_e32 v57, v57, v95
	v_cndmask_b32_e64 v138, 1.0, v111, s[10:11]
	v_mul_f32_e32 v104, v104, v138
	v_mul_f32_e32 v46, v46, v138
	v_mul_f32_e32 v47, v47, v138
	v_mul_f32_e32 v44, v44, v138
	v_mul_f32_e32 v45, v45, v138
	v_mul_f32_e32 v42, v42, v138
	v_mul_f32_e32 v43, v43, v138
	v_mul_f32_e32 v40, v40, v138
	v_mul_f32_e32 v41, v41, v138
	v_mul_f32_e32 v38, v38, v138
	v_mul_f32_e32 v39, v39, v138
	v_mul_f32_e32 v36, v36, v138
	v_mul_f32_e32 v37, v37, v138
	v_mul_f32_e32 v34, v34, v138
	v_mul_f32_e32 v35, v35, v138
	v_mul_f32_e32 v32, v32, v138
	v_mul_f32_e32 v33, v33, v138
	v_sub_f32_e32 v58, v58, v95
	v_sub_f32_e32 v59, v59, v95
	v_sub_f32_e32 v60, v60, v95
	v_sub_f32_e32 v61, v61, v95
	v_sub_f32_e32 v62, v62, v95
	v_sub_f32_e32 v63, v63, v95
	v_sub_f32_e32 v64, v64, v95
	v_sub_f32_e32 v65, v65, v95
	v_sub_f32_e32 v66, v66, v95
	v_sub_f32_e32 v67, v67, v95
	v_sub_f32_e32 v68, v68, v95
	v_sub_f32_e32 v69, v69, v95
	v_sub_f32_e32 v70, v70, v95
	v_sub_f32_e32 v71, v71, v95
	v_mov_b32_e32 v111, v133
.LBB0_1007:
	v_cmp_le_u32_e32 vcc, v96, v116
	s_nop 1
	v_cndmask_b32_e32 v72, v183, v72, vcc
	v_cmp_le_u32_e32 vcc, v97, v116
	s_nop 1
	v_cndmask_b32_e32 v73, v183, v73, vcc
	v_cmp_le_u32_e32 vcc, v98, v116
	v_max3_f32 v95, v72, s78, v73
	s_nop 0
	v_cndmask_b32_e32 v74, v183, v74, vcc
	v_cmp_le_u32_e32 vcc, v99, v116
	s_nop 1
	v_cndmask_b32_e32 v75, v183, v75, vcc
	v_cmp_le_u32_e32 vcc, v100, v116
	v_max3_f32 v95, v95, v74, v75
	s_nop 0
	v_cndmask_b32_e32 v76, v183, v76, vcc
	v_cmp_le_u32_e32 vcc, v101, v116
	s_nop 1
	v_cndmask_b32_e32 v77, v183, v77, vcc
	v_cmp_le_u32_e32 vcc, v102, v116
	v_max3_f32 v95, v95, v76, v77
	s_nop 0
	v_cndmask_b32_e32 v78, v183, v78, vcc
	v_cmp_le_u32_e32 vcc, v103, v116
	s_nop 1
	v_cndmask_b32_e32 v79, v183, v79, vcc
	v_cmp_le_u32_e32 vcc, v134, v116
	v_max3_f32 v95, v95, v78, v79
	s_nop 0
	v_cndmask_b32_e32 v80, v183, v80, vcc
	v_cmp_le_u32_e32 vcc, v88, v116
	s_nop 1
	v_cndmask_b32_e32 v81, v183, v81, vcc
	v_cmp_le_u32_e32 vcc, v89, v116
	v_max3_f32 v88, v95, v80, v81
	s_nop 0
	v_cndmask_b32_e32 v82, v183, v82, vcc
	v_cmp_le_u32_e32 vcc, v90, v116
	s_nop 1
	v_cndmask_b32_e32 v83, v183, v83, vcc
	v_cmp_le_u32_e32 vcc, v91, v116
	v_max3_f32 v88, v88, v82, v83
	s_nop 0
	v_cndmask_b32_e32 v84, v183, v84, vcc
	v_cmp_le_u32_e32 vcc, v92, v116
	s_nop 1
	v_cndmask_b32_e32 v85, v183, v85, vcc
	v_cmp_le_u32_e32 vcc, v93, v116
	v_max3_f32 v88, v88, v84, v85
	s_nop 0
	v_cndmask_b32_e32 v86, v183, v86, vcc
	v_cmp_le_u32_e32 vcc, v94, v116
	s_nop 1
	v_cndmask_b32_e32 v87, v183, v87, vcc
	v_max3_f32 v88, v88, v86, v87
	v_mov_b32_e32 v89, v88
	s_nop 1
	v_permlane16_swap_b32_e32 v88, v89
	v_max_f32_e32 v89, v89, v89
	v_max_f32_e32 v88, v88, v88
	v_max_f32_e32 v88, v88, v89
	v_mov_b32_e32 v89, v88
	s_nop 1
	v_permlane32_swap_b32_e32 v88, v89
	v_max_f32_e32 v89, v89, v89
	v_max_f32_e32 v88, v88, v88
	v_max_f32_e32 v88, v88, v89
	v_cmp_lt_f32_e32 vcc, s80, v88
	s_nop 1
	v_cndmask_b32_e64 v89, 0, 1, vcc
	v_cmp_lt_f32_e32 vcc, s77, v88
	s_nop 1
	v_cndmask_b32_e64 v90, 0, 1, vcc
	v_cndmask_b32_e64 v89, v90, v89, s[8:9]
	v_and_b32_e32 v89, 1, v89
	v_cmp_eq_u32_e64 s[8:9], 1, v89
	v_cmp_ne_u32_e32 vcc, 0, v89
	s_cbranch_vccz .LBB0_1009
	v_add_f32_e32 v89, v132, v88
	v_cndmask_b32_e64 v89, v110, v89, s[8:9]
	v_sub_f32_e32 v90, v110, v89
	v_exp_f32_e32 v90, v90
	v_cndmask_b32_e64 v88, 0, v88, s[8:9]
	v_sub_f32_e32 v72, v72, v88
	v_sub_f32_e32 v73, v73, v88
	v_cndmask_b32_e64 v90, 1.0, v90, s[8:9]
	v_mul_f32_e32 v105, v105, v90
	v_mul_f32_e32 v30, v30, v90
	v_mul_f32_e32 v31, v31, v90
	v_mul_f32_e32 v28, v28, v90
	v_mul_f32_e32 v29, v29, v90
	v_mul_f32_e32 v26, v26, v90
	v_mul_f32_e32 v27, v27, v90
	v_mul_f32_e32 v24, v24, v90
	v_mul_f32_e32 v25, v25, v90
	v_mul_f32_e32 v22, v22, v90
	v_mul_f32_e32 v23, v23, v90
	v_mul_f32_e32 v20, v20, v90
	v_mul_f32_e32 v21, v21, v90
	v_mul_f32_e32 v18, v18, v90
	v_mul_f32_e32 v19, v19, v90
	v_mul_f32_e32 v16, v16, v90
	v_mul_f32_e32 v17, v17, v90
	v_sub_f32_e32 v74, v74, v88
	v_sub_f32_e32 v75, v75, v88
	v_sub_f32_e32 v76, v76, v88
	v_sub_f32_e32 v77, v77, v88
	v_sub_f32_e32 v78, v78, v88
	v_sub_f32_e32 v79, v79, v88
	v_sub_f32_e32 v80, v80, v88
	v_sub_f32_e32 v81, v81, v88
	v_sub_f32_e32 v82, v82, v88
	v_sub_f32_e32 v83, v83, v88
	v_sub_f32_e32 v84, v84, v88
	v_sub_f32_e32 v85, v85, v88
	v_sub_f32_e32 v86, v86, v88
	v_sub_f32_e32 v87, v87, v88
	v_mov_b32_e32 v110, v89

; #define LAS __attribute__((address_space(3)))
; __device__ __forceinline__ unsigned cvtpk(float lo, float hi) { f32x2_t v = {lo, hi}; bf16x2_t b = __builtin_convertvector(v, bf16x2_t); return __builtin_bit_cast(unsigned, b); }
; template <int I0, int NQ, int VO> __device__ __forceinline__ void tile_y(LAS unsigned char* lds, float (&l)[2], f32x4 (&o)[2][4], f32x4 (&s)[2][4], int fr, int fq) {
;     bf16x8 pb[NQ][2];
; #pragma unroll
;     for (int q = 0; q < NQ; ++q) {
;         f32x4 (&sq)[4] = s[I0 + q];
;         f32x2_t rs2 = {0.f, 0.f};
; #pragma unroll
;         for (int ss = 0; ss < 4; ++ss) {
; #pragma unroll
;             for (int i = 0; i < 4; ++i) sq[ss][i] = __builtin_amdgcn_exp2f(sq[ss][i]);
;             rs2 += (f32x2_t){sq[ss][0], sq[ss][1]}; rs2 += (f32x2_t){sq[ss][2], sq[ss][3]};
;         }
;         l[I0 + q] += rs2.x + rs2.y;
; #pragma unroll
;         for (int j = 0; j < 2; ++j) {
;             const v4u w = (v4u){cvtpk(sq[2 * j][0], sq[2 * j][1]), cvtpk(sq[2 * j][2], sq[2 * j][3]), cvtpk(sq[2 * j + 1][0], sq[2 * j + 1][1]), cvtpk(sq[2 * j + 1][2], sq[2 * j + 1][3])};
;             pb[q][j] = __builtin_bit_cast(bf16x8, w);
;         }
;     }
; #pragma unroll
;     for (int dt = 0; dt < 4; ++dt)
; #pragma unroll
;         for (int j = 0; j < 2; ++j) {
;             LAS unsigned char* vp = lds + VO + ((32 * j + 4 * fq + (fr >> 2)) * VSTR + 16 * dt + 4 * (fr & 3)) * 2;
;             const s16x4 lo = __builtin_bit_cast(s16x4, __builtin_amdgcn_ds_read_tr16_b64_v4i16((LAS v4i16_t*)vp));
;             const s16x4 hi = __builtin_bit_cast(s16x4, __builtin_amdgcn_ds_read_tr16_b64_v4i16((LAS v4i16_t*)(vp + 16 * VSTR * 2)));
;             const bf16x8 vf = (bf16x8){lo[0], lo[1], lo[2], lo[3], hi[0], hi[1], hi[2], hi[3]};
; #pragma unroll
;             for (int q = 0; q < NQ; ++q) o[I0 + q][dt] = __builtin_amdgcn_mfma_f32_16x16x32_bf16(vf, pb[q][j], o[I0 + q][dt], 0, 0, 0);
;         }
; }
.LBB0_1010:
	s_or_b64 exec, exec, s[60:61]
	s_waitcnt lgkmcnt(0)
	s_barrier
	s_and_saveexec_b64 s[8:9], s[6:7]
	s_cbranch_execz .LBB0_1012
	s_waitcnt lgkmcnt(0)
	v_add_u32_e32 v98, s87, v124
	ds_read_b64_tr_b16 v[96:97], v98 offset:8192
	ds_read_b64_tr_b16 v[98:99], v98 offset:10752
	v_add_u32_e32 v134, s87, v125
	v_exp_f32_e32 v56, v56
	v_exp_f32_e32 v57, v57
	v_exp_f32_e32 v58, v58
	v_exp_f32_e32 v59, v59
	v_exp_f32_e32 v60, v60
	v_exp_f32_e32 v61, v61
	v_exp_f32_e32 v62, v62
	v_exp_f32_e32 v63, v63
	v_exp_f32_e32 v72, v72
	v_exp_f32_e32 v73, v73
	v_exp_f32_e32 v74, v74
	v_exp_f32_e32 v75, v75
	v_exp_f32_e32 v76, v76
	v_exp_f32_e32 v77, v77
	v_exp_f32_e32 v78, v78
	v_exp_f32_e32 v79, v79
	ds_read_b64_tr_b16 v[132:133], v134 offset:8192
	ds_read_b64_tr_b16 v[134:135], v134 offset:10752
	v_exp_f32_e32 v64, v64
	v_exp_f32_e32 v65, v65
	v_exp_f32_e32 v66, v66
	v_exp_f32_e32 v67, v67
	v_exp_f32_e32 v68, v68
	v_exp_f32_e32 v69, v69
	v_exp_f32_e32 v70, v70
	v_exp_f32_e32 v71, v71
	v_cvt_pk_bf16_f32 v88, v56, v57
	v_cvt_pk_bf16_f32 v89, v58, v59
	v_cvt_pk_bf16_f32 v90, v60, v61
	v_cvt_pk_bf16_f32 v91, v62, v63
	v_exp_f32_e32 v80, v80
	v_exp_f32_e32 v81, v81
	v_exp_f32_e32 v82, v82
	v_exp_f32_e32 v83, v83
	v_exp_f32_e32 v84, v84
	v_exp_f32_e32 v85, v85
	v_exp_f32_e32 v86, v86
	v_exp_f32_e32 v87, v87
	v_cvt_pk_bf16_f32 v100, v72, v73
	v_cvt_pk_bf16_f32 v101, v74, v75
	v_cvt_pk_bf16_f32 v102, v76, v77
	v_cvt_pk_bf16_f32 v103, v78, v79
	v_add_u32_e32 v137, s87, v126
	s_waitcnt lgkmcnt(0)
	v_mfma_f32_16x16x32_bf16 v[44:47], v[96:99], v[88:91], v[44:47]
	ds_read_b64_tr_b16 v[156:157], v137 offset:8192
	v_cvt_pk_bf16_f32 v92, v64, v65
	v_cvt_pk_bf16_f32 v93, v66, v67
	v_mfma_f32_16x16x32_bf16 v[28:31], v[96:99], v[100:103], v[28:31]
	ds_read_b64_tr_b16 v[158:159], v137 offset:10752
	v_cvt_pk_bf16_f32 v94, v68, v69
	v_cvt_pk_bf16_f32 v95, v70, v71
	v_cvt_pk_bf16_f32 v138, v80, v81
	v_cvt_pk_bf16_f32 v139, v82, v83
	v_cvt_pk_bf16_f32 v140, v84, v85
	v_cvt_pk_bf16_f32 v141, v86, v87
	v_add_u32_e32 v98, s87, v127
	v_mfma_f32_16x16x32_bf16 v[44:47], v[132:135], v[92:95], v[44:47]
	ds_read_b64_tr_b16 v[96:97], v98 offset:8192
	v_add_u32_e32 v137, s87, v128
	v_mfma_f32_16x16x32_bf16 v[28:31], v[132:135], v[138:141], v[28:31]
	ds_read_b64_tr_b16 v[98:99], v98 offset:10752
	v_add_f32_e64 v134, v56, 0
	v_add_f32_e64 v135, v57, 0
	s_nop 0
	v_add_f32_e32 v134, v58, v134
	v_add_f32_e32 v135, v59, v135
	s_waitcnt lgkmcnt(0)
	v_mfma_f32_16x16x32_bf16 v[40:43], v[156:159], v[88:91], v[40:43]
	ds_read_b64_tr_b16 v[132:133], v137 offset:8192
	v_add_f32_e32 v142, v60, v134
	v_add_f32_e32 v143, v61, v135
	v_mfma_f32_16x16x32_bf16 v[24:27], v[156:159], v[100:103], v[24:27]
	ds_read_b64_tr_b16 v[134:135], v137 offset:10752
	v_add_u32_e32 v137, s87, v129
	v_add_f32_e32 v142, v62, v142
	v_add_f32_e32 v143, v63, v143
	v_mfma_f32_16x16x32_bf16 v[40:43], v[96:99], v[92:95], v[40:43]
	ds_read_b64_tr_b16 v[156:157], v137 offset:8192
	v_mfma_f32_16x16x32_bf16 v[24:27], v[96:99], v[138:141], v[24:27]
	ds_read_b64_tr_b16 v[158:159], v137 offset:10752
	v_add_f32_e32 v96, v64, v142
	v_add_f32_e32 v97, v65, v143
	v_add_u32_e32 v137, s87, v130
	v_add_f32_e32 v96, v66, v96
	v_add_f32_e32 v97, v67, v97
	s_waitcnt lgkmcnt(0)
	v_mfma_f32_16x16x32_bf16 v[36:39], v[132:135], v[88:91], v[36:39]
	v_add_f32_e64 v98, v68, v96
	v_add_f32_e64 v99, v69, v97
	ds_read_b64_tr_b16 v[96:97], v137 offset:8192
	v_add_f32_e32 v142, v70, v98
	v_add_f32_e32 v143, v71, v99
	v_mfma_f32_16x16x32_bf16 v[20:23], v[132:135], v[100:103], v[20:23]
	ds_read_b64_tr_b16 v[98:99], v137 offset:10752
	v_add_f32_e64 v132, v72, 0
	v_add_f32_e64 v133, v73, 0
	v_add_u32_e32 v137, s87, v131
	v_add_f32_e32 v134, v74, v132
	v_add_f32_e32 v135, v75, v133
	v_mfma_f32_16x16x32_bf16 v[36:39], v[156:159], v[92:95], v[36:39]
	v_add_f32_e64 v134, v76, v134
	v_add_f32_e64 v135, v77, v135
	ds_read_b64_tr_b16 v[132:133], v137 offset:8192
	v_mfma_f32_16x16x32_bf16 v[20:23], v[156:159], v[138:141], v[20:23]
	v_add_f32_e64 v156, v78, v134
	v_add_f32_e64 v157, v79, v135
	ds_read_b64_tr_b16 v[134:135], v137 offset:10752
	s_waitcnt lgkmcnt(0)
	v_mfma_f32_16x16x32_bf16 v[32:35], v[96:99], v[88:91], v[32:35]
	v_add_f32_e64 v88, v80, v156
	v_add_f32_e64 v89, v81, v157
	v_mov_b32_e32 v90, v142
	v_add_f32_e32 v88, v82, v88
	v_add_f32_e32 v89, v83, v89
	v_mfma_f32_16x16x32_bf16 v[16:19], v[96:99], v[100:103], v[16:19]
	v_add_f32_e64 v88, v84, v88
	v_add_f32_e64 v89, v85, v89
	v_add_f32_e32 v88, v86, v88
	v_add_f32_e32 v89, v87, v89
	v_mfma_f32_16x16x32_bf16 v[32:35], v[132:135], v[92:95], v[32:35]
	v_mov_b32_e32 v91, v88
	v_mov_b32_e32 v88, v143
	v_add_f32_e32 v88, v90, v88
	v_add_f32_e32 v89, v91, v89
	v_mfma_f32_16x16x32_bf16 v[16:19], v[132:135], v[138:141], v[16:19]
	v_add_f32_e64 v104, v104, v88
	v_add_f32_e64 v105, v105, v89

; #define LAS __attribute__((address_space(3)))
; #define IMX3(a, b, c) imax2(imax2((a), __builtin_bit_cast(int, (b))), __builtin_bit_cast(int, (c)))
; template <int DQK, int MODE, bool FULL, int I0, int NQ> __device__ __forceinline__ void tile_x(LAS unsigned char* lds, const bf16x8 (&qf)[2][DQK / 32], int kbase, const int (&tpos)[2], const bool (&rowsel)[2],
;         float (&m)[2], float (&l)[2], f32x4 (&o)[2][4], f32x4 (&s)[2][4], int fr, int fq) {
;     constexpr int NKS = DQK / 32;
;     float meff[NQ];
; #pragma unroll
;     for (int q = 0; q < NQ; ++q) { meff[q] = (m[I0 + q] > -1e29f) ? m[I0 + q] : 0.f; const float c = (MODE == SEL && !rowsel[I0 + q]) ? NEG : -meff[q];
; #pragma unroll
;         for (int ss = 0; ss < 4; ++ss) s[I0 + q][ss] = (f32x4){c, c, c, c}; }
; #pragma unroll
;     for (int ss = 0; ss < 4; ++ss)
; #pragma unroll
;         for (int ks = 0; ks < NKS; ++ks) {
;             const bf16x8 kf = *(const LAS bf16x8*)(lds + k_off<DQK>(16 * ss + fr, 4 * ks + fq));
; #pragma unroll
;             for (int q = 0; q < NQ; ++q) s[I0 + q][ss] = __builtin_amdgcn_mfma_f32_16x16x32_bf16(kf, qf[I0 + q][ks], s[I0 + q][ss], 0, 0, 0);
;         }
; #pragma unroll
;     for (int q = 0; q < NQ; ++q) {
;         f32x4 (&sq)[4] = s[I0 + q];
;         const float mo = m[I0 + q];
;         bool slow = true;
;         if (FULL) {
;             int ia = __builtin_bit_cast(int, sq[0][0]);
;     ...
;             ia = IMX3(ia, sq[0][1], sq[0][2]); ia = IMX3(ia, sq[0][3], sq[1][0]); ia = IMX3(ia, sq[1][1], sq[1][2]); ia = IMX3(ia, sq[1][3], sq[2][0]);
;             int ib = __builtin_bit_cast(int, sq[2][1]);
;             ib = IMX3(ib, sq[2][2], sq[2][3]); ib = IMX3(ib, sq[3][0], sq[3][1]); ib = IMX3(ib, sq[3][2], sq[3][3]);
;     ...
;             const bool big = !(mo > -1e29f) || (imax2(ia, ib) > __builtin_bit_cast(int, RESCALE_THR));
;             slow = __any(big ? 1 : 0) != 0;
;         }
;         if (slow) {
;             float mx;
;             if (FULL) {
;                 mx = fmaxf(fmaxf(sq[0][0], sq[0][1]), fmaxf(sq[0][2], sq[0][3]));
; #pragma unroll
;                 for (int ss = 1; ss < 4; ++ss) mx = fmaxf(mx, fmaxf(fmaxf(sq[ss][0], sq[ss][1]), fmaxf(sq[ss][2], sq[ss][3])));
;             } else {
;                 mx = NEG;
; #pragma unroll
;                 for (int ss = 0; ss < 4; ++ss)
; #pragma unroll
.LBB0_1199:
	s_mul_i32 s64, s63, 0x4800
	s_add_i32 s65, s64, 0
	v_cmp_le_u32_e64 s[6:7], s62, v136
	s_and_saveexec_b64 s[58:59], s[6:7]
	s_cbranch_execz .LBB0_1214
	v_add_u32_e32 v56, s65, v127
	s_add_i32 s8, s62, 63
	v_add_u32_e32 v151, v56, v128
	v_cmp_gt_u32_e32 vcc, s8, v113
	v_cmp_le_i32_e64 s[8:9], s62, v126
	v_add_u32_e32 v146, v56, v129
	s_waitcnt lgkmcnt(0)
	ds_read_b128 v[100:103], v151
	ds_read_b128 v[96:99], v146
	s_or_b64 s[10:11], vcc, s[8:9]
	v_cmp_lt_f32_e32 vcc, s77, v141
	v_cmp_lt_f32_e64 s[8:9], s77, v140
	s_nop 0
	v_cndmask_b32_e32 v143, 0, v141, vcc
	v_cndmask_b32_e64 v142, 0, v140, s[8:9]
	v_xor_b32_e32 v88, 0x80000000, v143
	v_xor_b32_e32 v92, 0x80000000, v142
	v_mov_b32_e32 v89, v88
	v_mov_b32_e32 v90, v88
	v_mov_b32_e32 v91, v88
	v_mov_b32_e32 v93, v92
	v_mov_b32_e32 v94, v92
	v_mov_b32_e32 v95, v92
	s_and_saveexec_b64 s[12:13], s[10:11]
	s_xor_b64 s[60:61], exec, s[12:13]
	s_cbranch_execz .LBB0_1206
	s_waitcnt lgkmcnt(0)
	v_mfma_f32_16x16x32_bf16 v[56:59], v[100:103], v[32:35], v[88:91]
	ds_read_b128 v[60:63], v151 offset:2048
	ds_read_b128 v[64:67], v151 offset:4096
	ds_read_b128 v[76:79], v146 offset:2048
	ds_read_b128 v[84:87], v151 offset:6144
	ds_read_b128 v[80:83], v146 offset:4096
	ds_read_b128 v[156:159], v146 offset:6144
	v_mfma_f32_16x16x32_bf16 v[68:71], v[100:103], v[40:43], v[92:95]
	v_add_u32_e32 v100, s62, v130
	v_add_u32_e32 v101, 0x200, v100
	v_cmp_le_u32_e64 s[10:11], v100, v114
	v_mfma_f32_16x16x32_bf16 v[56:59], v[96:99], v[36:39], v[56:59]
	v_cmp_gt_u32_e64 s[12:13], v101, v114
	s_and_b64 s[10:11], s[10:11], s[12:13]
	v_add_u32_e32 v102, 0x203, v100
	v_mfma_f32_16x16x32_bf16 v[72:75], v[96:99], v[44:47], v[68:71]
	v_add_u32_e32 v96, 0x201, v100
	s_nop 2
	v_cndmask_b32_e64 v56, v183, v56, s[10:11]
	v_cmp_lt_u32_e64 s[10:11], v100, v114
	v_cmp_gt_u32_e64 s[12:13], v96, v114
	s_waitcnt lgkmcnt(0)
	v_mfma_f32_16x16x32_bf16 v[68:71], v[60:63], v[32:35], v[88:91]
	s_and_b64 s[10:11], s[10:11], s[12:13]
	v_add_u32_e32 v97, 2, v100
	v_add_u32_e32 v98, 0x202, v100
	v_mfma_f32_16x16x32_bf16 v[60:63], v[60:63], v[40:43], v[92:95]
	v_cndmask_b32_e64 v57, v183, v57, s[10:11]
	v_cmp_le_u32_e64 s[10:11], v97, v114
	v_cmp_gt_u32_e64 s[12:13], v98, v114
	s_and_b64 s[10:11], s[10:11], s[12:13]
	v_add_u32_e32 v99, 3, v100
	v_cndmask_b32_e64 v58, v183, v58, s[10:11]
	v_cmp_le_u32_e64 s[10:11], v99, v114
	v_cmp_gt_u32_e64 s[12:13], v102, v114
	v_mfma_f32_16x16x32_bf16 v[68:71], v[76:79], v[36:39], v[68:71]
	s_and_b64 s[10:11], s[10:11], s[12:13]
	v_max3_f32 v103, v56, s78, v57
	v_cndmask_b32_e64 v59, v183, v59, s[10:11]
	v_mfma_f32_16x16x32_bf16 v[76:79], v[76:79], v[44:47], v[60:63]
	v_max3_f32 v153, v103, v58, v59
	v_add_u32_e32 v103, 16, v100
	v_add_u32_e32 v146, 0x210, v100
	v_mfma_f32_16x16x32_bf16 v[60:63], v[64:67], v[32:35], v[88:91]
	v_cmp_le_u32_e64 s[10:11], v103, v114
	v_cmp_gt_u32_e64 s[12:13], v146, v114
	s_and_b64 s[10:11], s[10:11], s[12:13]
	v_mfma_f32_16x16x32_bf16 v[64:67], v[64:67], v[40:43], v[92:95]
	v_add_u32_e32 v151, 17, v100
	v_add_u32_e32 v155, 34, v100
	v_mfma_f32_16x16x32_bf16 v[160:163], v[80:83], v[36:39], v[60:63]
	v_mfma_f32_16x16x32_bf16 v[80:83], v[80:83], v[44:47], v[64:67]
	s_nop 1
	v_cndmask_b32_e64 v60, v183, v68, s[10:11]
	v_cmp_le_u32_e64 s[10:11], v151, v114
	v_mfma_f32_16x16x32_bf16 v[62:65], v[84:87], v[32:35], v[88:91]
	s_nop 2
	v_add_u32_e32 v88, 0x211, v100
	v_cmp_gt_u32_e64 s[12:13], v88, v114
	s_and_b64 s[10:11], s[10:11], s[12:13]
	v_add_u32_e32 v89, 18, v100
	v_add_u32_e32 v90, 0x212, v100
	v_cndmask_b32_e64 v61, v183, v69, s[10:11]
	v_cmp_le_u32_e64 s[10:11], v89, v114
	v_cmp_gt_u32_e64 s[12:13], v90, v114
	v_mfma_f32_16x16x32_bf16 v[84:87], v[84:87], v[40:43], v[92:95]
	s_and_b64 s[10:11], s[10:11], s[12:13]
	v_add_u32_e32 v91, 19, v100
	v_max3_f32 v66, v153, v60, v61
	v_add_u32_e32 v92, 0x213, v100
	v_mfma_f32_16x16x32_bf16 v[164:167], v[156:159], v[36:39], v[62:65]
	v_cmp_gt_u32_e64 s[12:13], v92, v114
	v_add_u32_e32 v93, 32, v100
	v_add_u32_e32 v94, 0x220, v100
	v_cndmask_b32_e64 v62, v183, v70, s[10:11]
	v_cmp_le_u32_e64 s[10:11], v91, v114
	s_and_b64 s[10:11], s[10:11], s[12:13]
	v_cmp_gt_u32_e64 s[12:13], v94, v114
	v_cndmask_b32_e64 v63, v183, v71, s[10:11]
	v_cmp_le_u32_e64 s[10:11], v93, v114
	s_and_b64 s[10:11], s[10:11], s[12:13]
	v_add_u32_e32 v95, 33, v100
	v_add_u32_e32 v153, 0x221, v100
	v_cndmask_b32_e64 v64, v183, v160, s[10:11]
	v_cmp_le_u32_e64 s[10:11], v95, v114
	v_cmp_gt_u32_e64 s[12:13], v153, v114
	v_mfma_f32_16x16x32_bf16 v[84:87], v[156:159], v[44:47], v[84:87]
	s_and_b64 s[10:11], s[10:11], s[12:13]
	v_add_u32_e32 v156, 0x222, v100
	v_cndmask_b32_e64 v65, v183, v161, s[10:11]
	v_cmp_le_u32_e64 s[10:11], v155, v114
	v_cmp_gt_u32_e64 s[12:13], v156, v114
	v_max3_f32 v66, v66, v62, v63
	s_and_b64 s[10:11], s[10:11], s[12:13]
	v_add_u32_e32 v157, 35, v100
	v_add_u32_e32 v158, 0x223, v100
	v_max3_f32 v68, v66, v64, v65
	v_cndmask_b32_e64 v66, v183, v162, s[10:11]
	v_cmp_le_u32_e64 s[10:11], v157, v114
	v_cmp_gt_u32_e64 s[12:13], v158, v114
	s_and_b64 s[10:11], s[10:11], s[12:13]
	v_add_u32_e32 v159, 48, v100
	v_add_u32_e32 v160, 0x230, v100
	v_cndmask_b32_e64 v67, v183, v163, s[10:11]
	v_cmp_le_u32_e64 s[10:11], v159, v114
	v_cmp_gt_u32_e64 s[12:13], v160, v114
	s_and_b64 s[10:11], s[10:11], s[12:13]
	v_add_u32_e32 v161, 49, v100
	v_add_u32_e32 v162, 0x231, v100
	v_max3_f32 v70, v68, v66, v67
	v_cndmask_b32_e64 v68, v183, v164, s[10:11]
	v_cmp_le_u32_e64 s[10:11], v161, v114
	v_cmp_gt_u32_e64 s[12:13], v162, v114
	s_and_b64 s[10:11], s[10:11], s[12:13]
	v_add_u32_e32 v163, 50, v100
	v_add_u32_e32 v164, 0x232, v100
	v_cndmask_b32_e64 v69, v183, v165, s[10:11]
	v_cmp_le_u32_e64 s[10:11], v163, v114
	v_cmp_gt_u32_e64 s[12:13], v164, v114
	s_and_b64 s[10:11], s[10:11], s[12:13]
	v_max3_f32 v195, v70, v68, v69
	v_cndmask_b32_e64 v70, v183, v166, s[10:11]
	v_add_u32_e32 v165, 51, v100
	v_add_u32_e32 v166, 0x233, v100
	v_cmp_le_u32_e64 s[10:11], v165, v114
	v_cmp_gt_u32_e64 s[12:13], v166, v114
	s_and_b64 s[10:11], s[10:11], s[12:13]
	v_cndmask_b32_e64 v71, v183, v167, s[10:11]
	v_max3_f32 v167, v195, v70, v71
	v_mov_b32_e32 v195, v167
	s_nop 1
	v_permlane16_swap_b32_e32 v167, v195
	v_max_f32_e32 v195, v195, v195
	v_max_f32_e32 v167, v167, v167
	v_max_f32_e32 v167, v167, v195
	v_mov_b32_e32 v195, v167
	s_nop 1
	v_permlane32_swap_b32_e32 v167, v195
	v_max_f32_e32 v195, v195, v195
	v_max_f32_e32 v167, v167, v167
	v_max_f32_e32 v167, v167, v195
	v_cmp_lt_f32_e64 s[10:11], s80, v167
	s_nop 1
	v_cndmask_b32_e64 v195, 0, 1, s[10:11]
	v_cmp_lt_f32_e64 s[10:11], s77, v167
	s_nop 1
	v_cndmask_b32_e64 v196, 0, 1, s[10:11]
	v_cndmask_b32_e32 v195, v196, v195, vcc
	v_and_b32_e32 v195, 1, v195
	v_cmp_eq_u32_e64 s[10:11], 1, v195
	v_cmp_ne_u32_e32 vcc, 0, v195
	s_cbranch_vccz .LBB0_1203
; template <int DQK, int MODE, bool FULL, int I0, int NQ> __device__ __forceinline__ void tile_x(LAS unsigned char* lds, const bf16x8 (&qf)[2][DQK / 32], int kbase, const int (&tpos)[2], const bool (&rowsel)[2],
;         float (&m)[2], float (&l)[2], f32x4 (&o)[2][4], f32x4 (&s)[2][4], int fr, int fq) {
;     ...
;                 for (int ss = 0; ss < 4; ++ss)
; #pragma unroll
;                     for (int i = 0; i < 4; ++i) { const bool ok = key_ok<MODE>(kbase + 16 * ss + 4 * fq + i, tpos[I0 + q], rowsel[I0 + q]); const float v = ok ? sq[ss][i] : NEG; sq[ss][i] = v; mx = fmaxf(mx, v); }
;             }
;             mx = rows_max(mx);
;             const bool need = (mo > -1e29f) ? (mx > RESCALE_THR) : (mx > -1e29f);
;             if (__any(need ? 1 : 0)) {
;                 const float delta = need ? mx : 0.f; const float mnew = need ? meff[q] + delta : mo; const float alpha = need ? __builtin_amdgcn_exp2f(mo - mnew) : 1.0f;
;                 l[I0 + q] *= alpha; m[I0 + q] = mnew;
; #pragma unroll
;                 for (int dt = 0; dt < 4; ++dt) o[I0 + q][dt] = o[I0 + q][dt] * alpha;
; #pragma unroll
;                 for (int ss = 0; ss < 4; ++ss) sq[ss] = sq[ss] - delta;
;             }
	v_add_f32_e32 v143, v143, v167
	v_cndmask_b32_e64 v143, v141, v143, s[10:11]
	v_sub_f32_e32 v141, v141, v143
	v_exp_f32_e32 v141, v141
	s_nop 0
	v_cndmask_b32_e64 v196, 1.0, v141, s[10:11]
	v_cndmask_b32_e64 v141, 0, v167, s[10:11]
	v_mul_f32_e32 v105, v105, v196
	v_mul_f32_e32 v30, v30, v196
	v_mul_f32_e32 v31, v31, v196
	v_mul_f32_e32 v28, v28, v196
	v_mul_f32_e32 v29, v29, v196
	v_mul_f32_e32 v26, v26, v196
	v_mul_f32_e32 v27, v27, v196
	v_mul_f32_e32 v24, v24, v196
	v_mul_f32_e32 v25, v25, v196
	v_mul_f32_e32 v22, v22, v196
	v_mul_f32_e32 v23, v23, v196
	v_mul_f32_e32 v20, v20, v196
	v_mul_f32_e32 v21, v21, v196
	v_mul_f32_e32 v18, v18, v196
	v_mul_f32_e32 v19, v19, v196
	v_mul_f32_e32 v16, v16, v196
	v_mul_f32_e32 v17, v17, v196
	v_sub_f32_e32 v56, v56, v141
	v_sub_f32_e32 v57, v57, v141
	v_sub_f32_e32 v58, v58, v141
	v_sub_f32_e32 v59, v59, v141
	v_sub_f32_e32 v60, v60, v141
	v_sub_f32_e32 v61, v61, v141
	v_sub_f32_e32 v62, v62, v141
	v_sub_f32_e32 v63, v63, v141
	v_sub_f32_e32 v64, v64, v141
	v_sub_f32_e32 v65, v65, v141
	v_sub_f32_e32 v66, v66, v141
	v_sub_f32_e32 v67, v67, v141
	v_sub_f32_e32 v68, v68, v141
	v_sub_f32_e32 v69, v69, v141
	v_sub_f32_e32 v70, v70, v141
	v_sub_f32_e32 v71, v71, v141
	v_mov_b32_e32 v141, v143
.LBB0_1203:
	v_cmp_le_u32_e32 vcc, v100, v116
	v_cmp_gt_u32_e64 s[10:11], v101, v116
	s_and_b64 vcc, vcc, s[10:11]
	v_cndmask_b32_e32 v72, v183, v72, vcc
	v_cmp_lt_u32_e32 vcc, v100, v116
	v_cmp_gt_u32_e64 s[10:11], v96, v116
	s_and_b64 vcc, vcc, s[10:11]
	v_cndmask_b32_e32 v73, v183, v73, vcc
	v_cmp_le_u32_e32 vcc, v97, v116
	v_cmp_gt_u32_e64 s[10:11], v98, v116
	s_and_b64 vcc, vcc, s[10:11]
	v_cndmask_b32_e32 v74, v183, v74, vcc
	v_cmp_le_u32_e32 vcc, v99, v116
	v_cmp_gt_u32_e64 s[10:11], v102, v116
	s_and_b64 vcc, vcc, s[10:11]
	v_cndmask_b32_e32 v75, v183, v75, vcc
	v_cmp_le_u32_e32 vcc, v103, v116
	v_cmp_gt_u32_e64 s[10:11], v146, v116
	s_and_b64 vcc, vcc, s[10:11]
	v_cndmask_b32_e32 v76, v183, v76, vcc
	v_cmp_le_u32_e32 vcc, v151, v116
	v_cmp_gt_u32_e64 s[10:11], v88, v116
	s_and_b64 vcc, vcc, s[10:11]
	v_cndmask_b32_e32 v77, v183, v77, vcc
	v_cmp_le_u32_e32 vcc, v89, v116
	v_cmp_gt_u32_e64 s[10:11], v90, v116
	s_and_b64 vcc, vcc, s[10:11]
	v_cndmask_b32_e32 v78, v183, v78, vcc
	v_cmp_le_u32_e32 vcc, v91, v116
	v_cmp_gt_u32_e64 s[10:11], v92, v116
	s_and_b64 vcc, vcc, s[10:11]
	v_cndmask_b32_e32 v79, v183, v79, vcc
	v_cmp_le_u32_e32 vcc, v93, v116
	v_cmp_gt_u32_e64 s[10:11], v94, v116
	s_and_b64 vcc, vcc, s[10:11]
	v_cndmask_b32_e32 v80, v183, v80, vcc
	v_cmp_le_u32_e32 vcc, v95, v116
	v_cmp_gt_u32_e64 s[10:11], v153, v116
	s_and_b64 vcc, vcc, s[10:11]
	v_cndmask_b32_e32 v81, v183, v81, vcc
	v_cmp_le_u32_e32 vcc, v155, v116
	v_cmp_gt_u32_e64 s[10:11], v156, v116
	s_and_b64 vcc, vcc, s[10:11]
	v_cndmask_b32_e32 v82, v183, v82, vcc
	v_cmp_le_u32_e32 vcc, v157, v116
	v_cmp_gt_u32_e64 s[10:11], v158, v116
	s_and_b64 vcc, vcc, s[10:11]
	v_cndmask_b32_e32 v83, v183, v83, vcc
	v_cmp_le_u32_e32 vcc, v159, v116
	v_cmp_gt_u32_e64 s[10:11], v160, v116
	s_and_b64 vcc, vcc, s[10:11]
	v_max3_f32 v96, v72, s78, v73
	v_cndmask_b32_e32 v84, v183, v84, vcc
	v_cmp_le_u32_e32 vcc, v161, v116
	v_cmp_gt_u32_e64 s[10:11], v162, v116
	v_max3_f32 v96, v96, v74, v75
	s_and_b64 vcc, vcc, s[10:11]
	v_max3_f32 v88, v96, v76, v77
	v_cndmask_b32_e32 v85, v183, v85, vcc
	v_cmp_le_u32_e32 vcc, v163, v116
	v_cmp_gt_u32_e64 s[10:11], v164, v116
	v_max3_f32 v88, v88, v78, v79
	s_and_b64 vcc, vcc, s[10:11]
	v_max3_f32 v88, v88, v80, v81
	v_cndmask_b32_e32 v86, v183, v86, vcc
	v_cmp_le_u32_e32 vcc, v165, v116
	v_cmp_gt_u32_e64 s[10:11], v166, v116
	v_max3_f32 v88, v88, v82, v83
	s_and_b64 vcc, vcc, s[10:11]
	v_max3_f32 v88, v88, v84, v85
	v_cndmask_b32_e32 v87, v183, v87, vcc
	v_max3_f32 v88, v88, v86, v87
	v_mov_b32_e32 v89, v88
	s_nop 1
	v_permlane16_swap_b32_e32 v88, v89
	v_max_f32_e32 v89, v89, v89
	v_max_f32_e32 v88, v88, v88
	v_max_f32_e32 v88, v88, v89
	v_mov_b32_e32 v89, v88
	s_nop 1
	v_permlane32_swap_b32_e32 v88, v89
	v_max_f32_e32 v89, v89, v89
	v_max_f32_e32 v88, v88, v88
	v_max_f32_e32 v88, v88, v89
	v_cmp_lt_f32_e32 vcc, s80, v88
	s_nop 1
	v_cndmask_b32_e64 v89, 0, 1, vcc
	v_cmp_lt_f32_e32 vcc, s77, v88
	s_nop 1
	v_cndmask_b32_e64 v90, 0, 1, vcc
	v_cndmask_b32_e64 v89, v90, v89, s[8:9]
	v_and_b32_e32 v89, 1, v89
	v_cmp_eq_u32_e64 s[8:9], 1, v89
	v_cmp_ne_u32_e32 vcc, 0, v89
	s_cbranch_vccz .LBB0_1205
	v_add_f32_e32 v89, v142, v88
	v_cndmask_b32_e64 v89, v140, v89, s[8:9]
	v_sub_f32_e32 v90, v140, v89
	v_exp_f32_e32 v90, v90
	v_cndmask_b32_e64 v88, 0, v88, s[8:9]
	v_sub_f32_e32 v72, v72, v88
	v_sub_f32_e32 v73, v73, v88
	v_cndmask_b32_e64 v90, 1.0, v90, s[8:9]
	v_mul_f32_e32 v104, v104, v90
	v_mul_f32_e32 v14, v14, v90
	v_mul_f32_e32 v15, v15, v90
	v_mul_f32_e32 v12, v12, v90
	v_mul_f32_e32 v13, v13, v90
	v_mul_f32_e32 v10, v10, v90
	v_mul_f32_e32 v11, v11, v90
	v_mul_f32_e32 v8, v8, v90
	v_mul_f32_e32 v9, v9, v90
	v_mul_f32_e32 v6, v6, v90
	v_mul_f32_e32 v7, v7, v90
	v_mul_f32_e32 v4, v4, v90
	v_mul_f32_e32 v5, v5, v90
	v_mul_f32_e32 v2, v2, v90
	v_mul_f32_e32 v3, v3, v90
	v_mul_f32_e32 v0, v0, v90
	v_mul_f32_e32 v1, v1, v90
	v_sub_f32_e32 v74, v74, v88
	v_sub_f32_e32 v75, v75, v88
	v_sub_f32_e32 v76, v76, v88
	v_sub_f32_e32 v77, v77, v88
	v_sub_f32_e32 v78, v78, v88
	v_sub_f32_e32 v79, v79, v88
	v_sub_f32_e32 v80, v80, v88
	v_sub_f32_e32 v81, v81, v88
	v_sub_f32_e32 v82, v82, v88
	v_sub_f32_e32 v83, v83, v88
	v_sub_f32_e32 v84, v84, v88
	v_sub_f32_e32 v85, v85, v88
	v_sub_f32_e32 v86, v86, v88
	v_sub_f32_e32 v87, v87, v88
	v_mov_b32_e32 v140, v89
; #define LAS __attribute__((address_space(3)))
; #define IMX3(a, b, c) imax2(imax2((a), __builtin_bit_cast(int, (b))), __builtin_bit_cast(int, (c)))
; template <int DQK, int MODE, bool FULL, int I0, int NQ> __device__ __forceinline__ void tile_x(LAS unsigned char* lds, const bf16x8 (&qf)[2][DQK / 32], int kbase, const int (&tpos)[2], const bool (&rowsel)[2],
;         float (&m)[2], float (&l)[2], f32x4 (&o)[2][4], f32x4 (&s)[2][4], int fr, int fq) {
;     ...
;     for (int ss = 0; ss < 4; ++ss)
; #pragma unroll
;         for (int ks = 0; ks < NKS; ++ks) {
;             const bf16x8 kf = *(const LAS bf16x8*)(lds + k_off<DQK>(16 * ss + fr, 4 * ks + fq));
; #pragma unroll
;             for (int q = 0; q < NQ; ++q) s[I0 + q][ss] = __builtin_amdgcn_mfma_f32_16x16x32_bf16(kf, qf[I0 + q][ks], s[I0 + q][ss], 0, 0, 0);
;         }
; #pragma unroll
;     for (int q = 0; q < NQ; ++q) {
;         f32x4 (&sq)[4] = s[I0 + q];
;         const float mo = m[I0 + q];
;         bool slow = true;
;         if (FULL) {
;             int ia = __builtin_bit_cast(int, sq[0][0]);
;     ...
;             ia = IMX3(ia, sq[0][1], sq[0][2]); ia = IMX3(ia, sq[0][3], sq[1][0]); ia = IMX3(ia, sq[1][1], sq[1][2]); ia = IMX3(ia, sq[1][3], sq[2][0]);
;             int ib = __builtin_bit_cast(int, sq[2][1]);
;             ib = IMX3(ib, sq[2][2], sq[2][3]); ib = IMX3(ib, sq[3][0], sq[3][1]); ib = IMX3(ib, sq[3][2], sq[3][3]);
;     ...
;             const bool big = !(mo > -1e29f) || (imax2(ia, ib) > __builtin_bit_cast(int, RESCALE_THR));
;             slow = __any(big ? 1 : 0) != 0;
;         }
;         if (slow) {
;             float mx;
;             if (FULL) {
;                 mx = fmaxf(fmaxf(sq[0][0], sq[0][1]), fmaxf(sq[0][2], sq[0][3]));
; #pragma unroll
;                 for (int ss = 1; ss < 4; ++ss) mx = fmaxf(mx, fmaxf(fmaxf(sq[ss][0], sq[ss][1]), fmaxf(sq[ss][2], sq[ss][3])));
;             } else {
;                 mx = NEG;
; #pragma unroll
;                 for (int ss = 0; ss < 4; ++ss)
; #pragma unroll
;                     for (int i = 0; i < 4; ++i) { const bool ok = key_ok<MODE>(kbase + 16 * ss + 4 * fq + i, tpos[I0 + q], rowsel[I0 + q]); const float v = ok ? sq[ss][i] : NEG; sq[ss][i] = v; mx = fmaxf(mx, v); }
;             }
;             mx = rows_max(mx);
;             const bool need = (mo > -1e29f) ? (mx > RESCALE_THR) : (mx > -1e29f);
;             if (__any(need ? 1 : 0)) {
.LBB0_1205:
.LBB0_1206:
	s_andn2_saveexec_b64 s[10:11], s[60:61]
	s_cbranch_execz .LBB0_1213
	s_waitcnt lgkmcnt(0)
	v_mfma_f32_16x16x32_bf16 v[60:63], v[100:103], v[40:43], v[92:95]
	v_cmp_nlt_f32_e64 s[8:9], s77, v141
	v_mfma_f32_16x16x32_bf16 v[72:75], v[96:99], v[44:47], v[60:63]
	s_nop 5
	ds_read_b128 v[60:63], v151 offset:2048
	ds_read_b128 v[64:67], v151 offset:4096
	ds_read_b128 v[80:83], v146 offset:2048
	ds_read_b128 v[84:87], v151 offset:6144
	v_mfma_f32_16x16x32_bf16 v[56:59], v[100:103], v[32:35], v[88:91]
	s_waitcnt lgkmcnt(0)
	v_mfma_f32_16x16x32_bf16 v[68:71], v[60:63], v[32:35], v[88:91]
	v_mfma_f32_16x16x32_bf16 v[56:59], v[96:99], v[36:39], v[56:59]
	ds_read_b128 v[96:99], v146 offset:4096
	ds_read_b128 v[100:103], v146 offset:6144
	v_mfma_f32_16x16x32_bf16 v[76:79], v[60:63], v[40:43], v[92:95]
	v_mfma_f32_16x16x32_bf16 v[60:63], v[80:83], v[36:39], v[68:71]
	v_mfma_f32_16x16x32_bf16 v[68:71], v[64:67], v[32:35], v[88:91]
	v_mfma_f32_16x16x32_bf16 v[76:79], v[80:83], v[44:47], v[76:79]
	v_mfma_f32_16x16x32_bf16 v[80:83], v[64:67], v[40:43], v[92:95]
	s_waitcnt lgkmcnt(0)
	v_mfma_f32_16x16x32_bf16 v[64:67], v[96:99], v[36:39], v[68:71]
	v_mfma_f32_16x16x32_bf16 v[68:71], v[84:87], v[32:35], v[88:91]
	v_mfma_f32_16x16x32_bf16 v[84:87], v[84:87], v[40:43], v[92:95]
	s_nop 1
	v_max_i32_e32 v88, v56, v60
	v_mfma_f32_16x16x32_bf16 v[68:71], v[100:103], v[36:39], v[68:71]
	v_mfma_f32_16x16x32_bf16 v[80:83], v[96:99], v[44:47], v[80:83]
	v_mfma_f32_16x16x32_bf16 v[84:87], v[100:103], v[44:47], v[84:87]
	s_nop 5
	v_max3_i32 v88, v64, v68, v88
	v_cmp_lt_i32_e32 vcc, s80, v88
	s_or_b64 vcc, s[8:9], vcc
	s_cbranch_vccz .LBB0_1210
	v_max_f32_e32 v88, v57, v57
	v_max_f32_e32 v89, v56, v56
	v_max_f32_e32 v88, v89, v88
	v_max_f32_e32 v89, v59, v59
	v_max_f32_e32 v90, v58, v58
	v_max_f32_e32 v89, v90, v89
	v_max_f32_e32 v90, v63, v63
	v_max_f32_e32 v91, v62, v62
	v_max_f32_e32 v90, v91, v90
	v_max3_f32 v90, v60, v61, v90
	v_max3_f32 v88, v88, v89, v90
	v_max_f32_e32 v89, v67, v67
	v_max_f32_e32 v90, v66, v66
	v_max_f32_e32 v89, v90, v89
	v_max_f32_e32 v90, v71, v71
	v_max_f32_e32 v91, v70, v70
	v_max_f32_e32 v90, v91, v90
	v_max3_f32 v89, v64, v65, v89
	v_max3_f32 v90, v68, v69, v90
	v_max3_f32 v88, v88, v89, v90
	v_mov_b32_e32 v89, v88
	s_nop 1
	v_permlane16_swap_b32_e32 v88, v89
	v_max_f32_e32 v89, v89, v89
	v_max_f32_e32 v88, v88, v88
	v_max_f32_e32 v88, v88, v89
	v_mov_b32_e32 v89, v88
	s_nop 1
	v_permlane32_swap_b32_e32 v88, v89
	v_max_f32_e32 v89, v89, v89
	v_max_f32_e32 v88, v88, v88
	v_max_f32_e32 v88, v88, v89
	v_cmp_lt_f32_e32 vcc, s77, v88
	s_nop 1
	v_cndmask_b32_e64 v89, 0, 1, vcc
	v_cmp_lt_f32_e32 vcc, s80, v88
	s_nop 1
	v_cndmask_b32_e64 v90, 0, 1, vcc
	v_cndmask_b32_e64 v89, v90, v89, s[8:9]
	v_and_b32_e32 v89, 1, v89
	v_cmp_eq_u32_e64 s[8:9], 1, v89
	v_cmp_ne_u32_e32 vcc, 0, v89
	s_cbranch_vccz .LBB0_1210
	v_add_f32_e32 v89, v143, v88
	v_cndmask_b32_e64 v89, v141, v89, s[8:9]
	v_sub_f32_e32 v90, v141, v89
	v_exp_f32_e32 v90, v90
	v_cndmask_b32_e64 v88, 0, v88, s[8:9]
	v_sub_f32_e32 v56, v56, v88
	v_sub_f32_e32 v57, v57, v88
	v_cndmask_b32_e64 v90, 1.0, v90, s[8:9]
	v_mul_f32_e32 v105, v105, v90
	v_mul_f32_e32 v30, v30, v90
	v_mul_f32_e32 v31, v31, v90
	v_mul_f32_e32 v28, v28, v90
	v_mul_f32_e32 v29, v29, v90
	v_mul_f32_e32 v26, v26, v90
	v_mul_f32_e32 v27, v27, v90
	v_mul_f32_e32 v24, v24, v90
	v_mul_f32_e32 v25, v25, v90
	v_mul_f32_e32 v22, v22, v90
	v_mul_f32_e32 v23, v23, v90
	v_mul_f32_e32 v20, v20, v90
	v_mul_f32_e32 v21, v21, v90
	v_mul_f32_e32 v18, v18, v90
	v_mul_f32_e32 v19, v19, v90
	v_mul_f32_e32 v16, v16, v90
	v_mul_f32_e32 v17, v17, v90
	v_sub_f32_e32 v58, v58, v88
	v_sub_f32_e32 v59, v59, v88
	v_sub_f32_e32 v60, v60, v88
	v_sub_f32_e32 v61, v61, v88
	v_sub_f32_e32 v62, v62, v88
	v_sub_f32_e32 v63, v63, v88
	v_sub_f32_e32 v64, v64, v88
	v_sub_f32_e32 v65, v65, v88
	v_sub_f32_e32 v66, v66, v88
	v_sub_f32_e32 v67, v67, v88
	v_sub_f32_e32 v68, v68, v88
	v_sub_f32_e32 v69, v69, v88
	v_sub_f32_e32 v70, v70, v88
	v_sub_f32_e32 v71, v71, v88
	v_mov_b32_e32 v141, v89
.LBB0_1210:
	v_max_i32_e32 v88, v72, v76
	v_max3_i32 v88, v80, v84, v88
	v_cmp_nlt_f32_e64 s[8:9], s77, v140
	v_cmp_lt_i32_e32 vcc, s80, v88
	s_or_b64 vcc, s[8:9], vcc
	s_cbranch_vccz .LBB0_1213
	v_max_f32_e32 v88, v73, v73
	v_max_f32_e32 v89, v72, v72
	v_max_f32_e32 v88, v89, v88
	v_max_f32_e32 v89, v75, v75
	v_max_f32_e32 v90, v74, v74
	v_max_f32_e32 v89, v90, v89
	v_max_f32_e32 v90, v79, v79
	v_max_f32_e32 v91, v78, v78
	v_max_f32_e32 v90, v91, v90
	v_max3_f32 v90, v76, v77, v90
	v_max3_f32 v88, v88, v89, v90
	v_max_f32_e32 v89, v83, v83
	v_max_f32_e32 v90, v82, v82
	v_max_f32_e32 v89, v90, v89
	v_max_f32_e32 v90, v87, v87
	v_max_f32_e32 v91, v86, v86
	v_max_f32_e32 v90, v91, v90
	v_max3_f32 v89, v80, v81, v89
	v_max3_f32 v90, v84, v85, v90
	v_max3_f32 v88, v88, v89, v90
	v_mov_b32_e32 v89, v88
	s_nop 1
	v_permlane16_swap_b32_e32 v88, v89
	v_max_f32_e32 v89, v89, v89
	v_max_f32_e32 v88, v88, v88
	v_max_f32_e32 v88, v88, v89
	v_mov_b32_e32 v89, v88
	s_nop 1
	v_permlane32_swap_b32_e32 v88, v89
	v_max_f32_e32 v89, v89, v89
	v_max_f32_e32 v88, v88, v88
	v_max_f32_e32 v88, v88, v89
	v_cmp_lt_f32_e32 vcc, s77, v88
	s_nop 1
	v_cndmask_b32_e64 v89, 0, 1, vcc
	v_cmp_lt_f32_e32 vcc, s80, v88
	s_nop 1
	v_cndmask_b32_e64 v90, 0, 1, vcc
	v_cndmask_b32_e64 v89, v90, v89, s[8:9]
	v_and_b32_e32 v89, 1, v89
	v_cmp_eq_u32_e64 s[8:9], 1, v89
	v_cmp_ne_u32_e32 vcc, 0, v89
	s_cbranch_vccz .LBB0_1213
	v_add_f32_e32 v89, v142, v88
	v_cndmask_b32_e64 v89, v140, v89, s[8:9]
	v_sub_f32_e32 v90, v140, v89
	v_exp_f32_e32 v90, v90
	v_cndmask_b32_e64 v88, 0, v88, s[8:9]
	v_sub_f32_e32 v72, v72, v88
	v_sub_f32_e32 v73, v73, v88
	v_cndmask_b32_e64 v90, 1.0, v90, s[8:9]
	v_mul_f32_e32 v104, v104, v90
	v_mul_f32_e32 v14, v14, v90
	v_mul_f32_e32 v15, v15, v90
	v_mul_f32_e32 v12, v12, v90
	v_mul_f32_e32 v13, v13, v90
	v_mul_f32_e32 v10, v10, v90
	v_mul_f32_e32 v11, v11, v90
	v_mul_f32_e32 v8, v8, v90
	v_mul_f32_e32 v9, v9, v90
	v_mul_f32_e32 v6, v6, v90
	v_mul_f32_e32 v7, v7, v90
	v_mul_f32_e32 v4, v4, v90
	v_mul_f32_e32 v5, v5, v90
	v_mul_f32_e32 v2, v2, v90
	v_mul_f32_e32 v3, v3, v90
	v_mul_f32_e32 v0, v0, v90
	v_mul_f32_e32 v1, v1, v90
	v_sub_f32_e32 v74, v74, v88
	v_sub_f32_e32 v75, v75, v88
	v_sub_f32_e32 v76, v76, v88
	v_sub_f32_e32 v77, v77, v88
	v_sub_f32_e32 v78, v78, v88
	v_sub_f32_e32 v79, v79, v88
	v_sub_f32_e32 v80, v80, v88
	v_sub_f32_e32 v81, v81, v88
	v_sub_f32_e32 v82, v82, v88
	v_sub_f32_e32 v83, v83, v88
	v_sub_f32_e32 v84, v84, v88
	v_sub_f32_e32 v85, v85, v88
	v_sub_f32_e32 v86, v86, v88
	v_sub_f32_e32 v87, v87, v88
	v_mov_b32_e32 v140, v89

; #define LAS __attribute__((address_space(3)))
; __device__ __forceinline__ unsigned cvtpk(float lo, float hi) { f32x2_t v = {lo, hi}; bf16x2_t b = __builtin_convertvector(v, bf16x2_t); return __builtin_bit_cast(unsigned, b); }
; template <int I0, int NQ, int VO> __device__ __forceinline__ void tile_y(LAS unsigned char* lds, float (&l)[2], f32x4 (&o)[2][4], f32x4 (&s)[2][4], int fr, int fq) {
;     bf16x8 pb[NQ][2];
; #pragma unroll
;     for (int q = 0; q < NQ; ++q) {
;         f32x4 (&sq)[4] = s[I0 + q];
;         f32x2_t rs2 = {0.f, 0.f};
; #pragma unroll
;         for (int ss = 0; ss < 4; ++ss) {
; #pragma unroll
;             for (int i = 0; i < 4; ++i) sq[ss][i] = __builtin_amdgcn_exp2f(sq[ss][i]);
;             rs2 += (f32x2_t){sq[ss][0], sq[ss][1]}; rs2 += (f32x2_t){sq[ss][2], sq[ss][3]};
;         }
;         l[I0 + q] += rs2.x + rs2.y;
; #pragma unroll
;         for (int j = 0; j < 2; ++j) {
;             const v4u w = (v4u){cvtpk(sq[2 * j][0], sq[2 * j][1]), cvtpk(sq[2 * j][2], sq[2 * j][3]), cvtpk(sq[2 * j + 1][0], sq[2 * j + 1][1]), cvtpk(sq[2 * j + 1][2], sq[2 * j + 1][3])};
;             pb[q][j] = __builtin_bit_cast(bf16x8, w);
;         }
;     }
; #pragma unroll
;     for (int dt = 0; dt < 4; ++dt)
; #pragma unroll
;         for (int j = 0; j < 2; ++j) {
;             LAS unsigned char* vp = lds + VO + ((32 * j + 4 * fq + (fr >> 2)) * VSTR + 16 * dt + 4 * (fr & 3)) * 2;
;             const s16x4 lo = __builtin_bit_cast(s16x4, __builtin_amdgcn_ds_read_tr16_b64_v4i16((LAS v4i16_t*)vp));
;             const s16x4 hi = __builtin_bit_cast(s16x4, __builtin_amdgcn_ds_read_tr16_b64_v4i16((LAS v4i16_t*)(vp + 16 * VSTR * 2)));
;             const bf16x8 vf = (bf16x8){lo[0], lo[1], lo[2], lo[3], hi[0], hi[1], hi[2], hi[3]};
; #pragma unroll
;             for (int q = 0; q < NQ; ++q) o[I0 + q][dt] = __builtin_amdgcn_mfma_f32_16x16x32_bf16(vf, pb[q][j], o[I0 + q][dt], 0, 0, 0);
;         }
; }
.LBB0_1214:
	s_or_b64 exec, exec, s[58:59]
	s_waitcnt lgkmcnt(0)
	s_barrier
	s_and_saveexec_b64 s[8:9], s[6:7]
	s_cbranch_execz .LBB0_1216
	s_waitcnt lgkmcnt(0)
	v_add_u32_e32 v98, s65, v131
	ds_read_b64_tr_b16 v[96:97], v98 offset:8192
	ds_read_b64_tr_b16 v[98:99], v98 offset:10752
	v_add_u32_e32 v142, s65, v132
	v_exp_f32_e32 v56, v56
	v_exp_f32_e32 v57, v57
	v_exp_f32_e32 v58, v58
	v_exp_f32_e32 v59, v59
	v_exp_f32_e32 v60, v60
	v_exp_f32_e32 v61, v61
	v_exp_f32_e32 v62, v62
	v_exp_f32_e32 v63, v63
	v_exp_f32_e32 v72, v72
	v_exp_f32_e32 v73, v73
	v_exp_f32_e32 v74, v74
	v_exp_f32_e32 v75, v75
	v_exp_f32_e32 v76, v76
	v_exp_f32_e32 v77, v77
	v_exp_f32_e32 v78, v78
	v_exp_f32_e32 v79, v79
	ds_read_b64_tr_b16 v[156:157], v142 offset:8192
	ds_read_b64_tr_b16 v[158:159], v142 offset:10752
	v_exp_f32_e32 v64, v64
	v_exp_f32_e32 v65, v65
	v_exp_f32_e32 v66, v66
	v_exp_f32_e32 v67, v67
	v_exp_f32_e32 v68, v68
	v_exp_f32_e32 v69, v69
	v_exp_f32_e32 v70, v70
	v_exp_f32_e32 v71, v71
	v_cvt_pk_bf16_f32 v88, v56, v57
	v_cvt_pk_bf16_f32 v89, v58, v59
	v_cvt_pk_bf16_f32 v90, v60, v61
	v_cvt_pk_bf16_f32 v91, v62, v63
	v_exp_f32_e32 v80, v80
	v_exp_f32_e32 v81, v81
	v_exp_f32_e32 v82, v82
	v_exp_f32_e32 v83, v83
	v_exp_f32_e32 v84, v84
	v_exp_f32_e32 v85, v85
	v_exp_f32_e32 v86, v86
	v_exp_f32_e32 v87, v87
	v_cvt_pk_bf16_f32 v100, v72, v73
	v_cvt_pk_bf16_f32 v101, v74, v75
	v_cvt_pk_bf16_f32 v102, v76, v77
	v_cvt_pk_bf16_f32 v103, v78, v79
	v_add_u32_e32 v142, s65, v133
	s_waitcnt lgkmcnt(0)
	v_mfma_f32_16x16x32_bf16 v[28:31], v[96:99], v[88:91], v[28:31]
	ds_read_b64_tr_b16 v[164:165], v142 offset:8192
	v_cvt_pk_bf16_f32 v92, v64, v65
	v_cvt_pk_bf16_f32 v93, v66, v67
	v_mfma_f32_16x16x32_bf16 v[12:15], v[96:99], v[100:103], v[12:15]
	ds_read_b64_tr_b16 v[166:167], v142 offset:10752
	v_cvt_pk_bf16_f32 v94, v68, v69
	v_cvt_pk_bf16_f32 v95, v70, v71
	v_cvt_pk_bf16_f32 v160, v80, v81
	v_cvt_pk_bf16_f32 v161, v82, v83
	v_cvt_pk_bf16_f32 v162, v84, v85
	v_cvt_pk_bf16_f32 v163, v86, v87
	v_add_u32_e32 v98, s65, v134
	v_mfma_f32_16x16x32_bf16 v[28:31], v[156:159], v[92:95], v[28:31]
	ds_read_b64_tr_b16 v[96:97], v98 offset:8192
	v_add_u32_e32 v146, s65, v135
	v_add_f32_e64 v142, v56, 0
	v_add_f32_e64 v143, v57, 0
	v_mfma_f32_16x16x32_bf16 v[12:15], v[156:159], v[160:163], v[12:15]
	ds_read_b64_tr_b16 v[98:99], v98 offset:10752
	v_add_f32_e32 v142, v58, v142
	v_add_f32_e32 v143, v59, v143
	s_waitcnt lgkmcnt(0)
	v_mfma_f32_16x16x32_bf16 v[24:27], v[164:167], v[88:91], v[24:27]
	ds_read_b64_tr_b16 v[156:157], v146 offset:8192
	v_add_f32_e32 v142, v60, v142
	v_add_f32_e32 v143, v61, v143
	v_mfma_f32_16x16x32_bf16 v[8:11], v[164:167], v[100:103], v[8:11]
	ds_read_b64_tr_b16 v[158:159], v146 offset:10752
	v_add_u32_e32 v146, s65, v137
	v_add_f32_e32 v142, v62, v142
	v_add_f32_e32 v143, v63, v143
	v_mfma_f32_16x16x32_bf16 v[24:27], v[96:99], v[92:95], v[24:27]
	ds_read_b64_tr_b16 v[164:165], v146 offset:8192
	v_mfma_f32_16x16x32_bf16 v[8:11], v[96:99], v[160:163], v[8:11]
	ds_read_b64_tr_b16 v[166:167], v146 offset:10752
	v_add_f32_e32 v96, v64, v142
	v_add_f32_e32 v97, v65, v143
	v_add_u32_e32 v146, s65, v138
	v_add_f32_e32 v96, v66, v96
	v_add_f32_e32 v97, v67, v97
	s_waitcnt lgkmcnt(0)
	v_mfma_f32_16x16x32_bf16 v[20:23], v[156:159], v[88:91], v[20:23]
	v_add_f32_e64 v98, v68, v96
	v_add_f32_e64 v99, v69, v97
	ds_read_b64_tr_b16 v[96:97], v146 offset:8192
	v_add_f32_e32 v142, v70, v98
	v_add_f32_e32 v143, v71, v99
	v_mfma_f32_16x16x32_bf16 v[4:7], v[156:159], v[100:103], v[4:7]
	ds_read_b64_tr_b16 v[98:99], v146 offset:10752
	v_add_f32_e64 v156, v72, 0
	v_add_f32_e64 v157, v73, 0
	v_add_u32_e32 v146, s65, v139
	v_add_f32_e32 v158, v74, v156
	v_add_f32_e32 v159, v75, v157
	v_mfma_f32_16x16x32_bf16 v[20:23], v[164:167], v[92:95], v[20:23]
	v_add_f32_e64 v158, v76, v158
	v_add_f32_e64 v159, v77, v159
	ds_read_b64_tr_b16 v[156:157], v146 offset:8192
	v_mfma_f32_16x16x32_bf16 v[4:7], v[164:167], v[160:163], v[4:7]
	v_add_f32_e64 v164, v78, v158
	v_add_f32_e64 v165, v79, v159
	ds_read_b64_tr_b16 v[158:159], v146 offset:10752
	s_waitcnt lgkmcnt(0)
	v_mfma_f32_16x16x32_bf16 v[16:19], v[96:99], v[88:91], v[16:19]
	v_add_f32_e64 v88, v80, v164
	v_add_f32_e64 v89, v81, v165
	v_mov_b32_e32 v91, v142
	v_add_f32_e32 v88, v82, v88
	v_add_f32_e32 v89, v83, v89
	v_mfma_f32_16x16x32_bf16 v[0:3], v[96:99], v[100:103], v[0:3]
	v_add_f32_e64 v88, v84, v88
	v_add_f32_e64 v89, v85, v89
	v_add_f32_e32 v88, v86, v88
	v_add_f32_e32 v89, v87, v89
	v_mfma_f32_16x16x32_bf16 v[16:19], v[156:159], v[92:95], v[16:19]
	v_mov_b32_e32 v90, v88
	v_mov_b32_e32 v142, v89
	v_add_f32_e32 v88, v90, v142
	v_add_f32_e32 v89, v91, v143
	v_mfma_f32_16x16x32_bf16 v[0:3], v[156:159], v[160:163], v[0:3]
	v_add_f32_e64 v104, v104, v88
	v_add_f32_e64 v105, v105, v89
